# grid barrier: non-leader workgroups poll the cross-XCD release generation directly instead of waiting for their XCD leader to forward it
# speedup vs baseline: 1.0011x; 1.0011x over previous
; __device__ __forceinline__ unsigned xb_ld(unsigned* p)              { return __hip_atomic_load(p, __ATOMIC_RELAXED, __HIP_MEMORY_SCOPE_AGENT); }
; __device__ __forceinline__ unsigned xb_add(unsigned* p, unsigned v) { return __hip_atomic_fetch_add(p, v, __ATOMIC_RELAXED, __HIP_MEMORY_SCOPE_AGENT); }
; #define XB_SPIN(cond, bar) do { unsigned _sp = 0; while (cond) { __builtin_amdgcn_s_sleep(1); \
;     if ((++_sp & 255u) == 0u) { if (xb_ld(&(bar)[XB_TMO])) break; if (_sp > XB_SPIN_CAP) { atomicAdd(&(bar)[XB_TMO], 1u); break; } } } } while (0)
; __device__ __forceinline__ void xcd_barrier(const XcdBarrier& b) {
;     ...
;         const unsigned old = xb_add(&bar[XB_XSUB(b.x)], 1u);
;         const unsigned gen = old / nloc;
;         if (old + 1u == (gen + 1u) * nloc) {
;             __builtin_amdgcn_fence(__ATOMIC_RELEASE, "agent");
;             asm volatile("s_waitcnt vmcnt(0)" ::: "memory");
;             const unsigned og = xb_add(&bar[XB_TOP], 1u);
;             const unsigned tg = og / nx;
;             if (og + 1u == (tg + 1u) * nx) xb_add(&bar[XB_TOPGEN], 1u);
;             else XB_SPIN(xb_ld(&bar[XB_TOPGEN]) == tg, bar);
;             __builtin_amdgcn_fence(__ATOMIC_ACQUIRE, "agent");
;             xb_add(&bar[XB_XGEN(b.x)], 1u);
;             asm volatile("s_waitcnt vmcnt(0)" ::: "memory");
;         } else {
;             XB_SPIN(xb_ld(&bar[XB_XGEN(b.x)]) == gen, bar);
;             __builtin_amdgcn_fence(__ATOMIC_ACQUIRE, "agent");
;             asm volatile("s_waitcnt vmcnt(0)" ::: "memory");
.LBB0_68:
	s_or_b64 exec, exec, s[10:11]
	v_cvt_f32_u32_e32 v5, v3
	s_waitcnt vmcnt(0)
	v_readfirstlane_b32 s8, v4
	v_sub_u32_e32 v4, 0, v3
	v_rcp_iflag_f32_e32 v5, v5
	v_add_u32_e32 v6, s8, v2
	v_mul_f32_e32 v5, 0x4f7ffffe, v5
	v_cvt_u32_f32_e32 v5, v5
	v_mul_lo_u32 v2, v4, v5
	v_mul_hi_u32 v2, v5, v2
	v_add_u32_e32 v2, v5, v2
	v_mul_hi_u32 v2, v6, v2
	v_mul_lo_u32 v4, v2, v3
	v_sub_u32_e32 v4, v6, v4
	v_add_u32_e32 v5, 1, v2
	v_cmp_ge_u32_e32 vcc, v4, v3
	s_nop 1
	v_cndmask_b32_e32 v2, v2, v5, vcc
	v_sub_u32_e32 v5, v4, v3
	v_cndmask_b32_e32 v4, v4, v5, vcc
	v_add_u32_e32 v5, 1, v2
	v_cmp_ge_u32_e32 vcc, v4, v3
	v_add_u32_e32 v4, 1, v6
	s_nop 0
	v_cndmask_b32_e32 v2, v2, v5, vcc
	v_mul_lo_u32 v5, v3, v2
	v_add_u32_e32 v3, v5, v3
	v_cmp_ne_u32_e32 vcc, v4, v3
	s_and_saveexec_b64 s[8:9], vcc
	s_xor_b64 s[8:9], exec, s[8:9]
	s_cbranch_execz .LBB0_82
	s_waitcnt lgkmcnt(0)
	v_mov_b32_e32 v1, 0x7100
	global_load_dword v1, v1, s[40:41] offset:1024 sc1
	s_add_u32 s14, s40, 0x7500
	s_addc_u32 s15, s41, 0
	s_waitcnt vmcnt(0)
	v_cmp_eq_u32_e32 vcc, v1, v2
	s_and_saveexec_b64 s[10:11], vcc
	s_cbranch_execz .LBB0_81
	s_add_u32 s12, s40, 0x4200
	s_addc_u32 s13, s41, 0
	s_mov_b32 s26, 1
	s_mov_b64 s[16:17], 0
	v_mov_b32_e32 v1, 0
	s_branch .LBB0_72

; __device__ __forceinline__ unsigned xb_ld(unsigned* p)              { return __hip_atomic_load(p, __ATOMIC_RELAXED, __HIP_MEMORY_SCOPE_AGENT); }
; __device__ __forceinline__ unsigned xb_add(unsigned* p, unsigned v) { return __hip_atomic_fetch_add(p, v, __ATOMIC_RELAXED, __HIP_MEMORY_SCOPE_AGENT); }
; #define XB_SPIN(cond, bar) do { unsigned _sp = 0; while (cond) { __builtin_amdgcn_s_sleep(1); \
;     if ((++_sp & 255u) == 0u) { if (xb_ld(&(bar)[XB_TMO])) break; if (_sp > XB_SPIN_CAP) { atomicAdd(&(bar)[XB_TMO], 1u); break; } } } } while (0)
; __device__ __forceinline__ void xcd_barrier(const XcdBarrier& b) {
;     ...
;         const unsigned old = xb_add(&bar[XB_XSUB(b.x)], 1u);
;         const unsigned gen = old / nloc;
;         if (old + 1u == (gen + 1u) * nloc) {
;             __builtin_amdgcn_fence(__ATOMIC_RELEASE, "agent");
;             asm volatile("s_waitcnt vmcnt(0)" ::: "memory");
;             const unsigned og = xb_add(&bar[XB_TOP], 1u);
;             const unsigned tg = og / nx;
;             if (og + 1u == (tg + 1u) * nx) xb_add(&bar[XB_TOPGEN], 1u);
;             else XB_SPIN(xb_ld(&bar[XB_TOPGEN]) == tg, bar);
;             __builtin_amdgcn_fence(__ATOMIC_ACQUIRE, "agent");
;             xb_add(&bar[XB_XGEN(b.x)], 1u);
;             asm volatile("s_waitcnt vmcnt(0)" ::: "memory");
;         } else {
;             XB_SPIN(xb_ld(&bar[XB_XGEN(b.x)]) == gen, bar);
;             __builtin_amdgcn_fence(__ATOMIC_ACQUIRE, "agent");
;             asm volatile("s_waitcnt vmcnt(0)" ::: "memory");
.LBB0_141:
	s_or_b64 exec, exec, s[12:13]
	v_cvt_f32_u32_e32 v4, v2
	s_waitcnt vmcnt(0)
	v_readfirstlane_b32 s10, v3
	v_sub_u32_e32 v3, 0, v2
	v_rcp_iflag_f32_e32 v4, v4
	v_add_u32_e32 v5, s10, v1
	v_mul_f32_e32 v4, 0x4f7ffffe, v4
	v_cvt_u32_f32_e32 v4, v4
	v_mul_lo_u32 v1, v3, v4
	v_mul_hi_u32 v1, v4, v1
	v_add_u32_e32 v1, v4, v1
	v_mul_hi_u32 v1, v5, v1
	v_mul_lo_u32 v3, v1, v2
	v_sub_u32_e32 v3, v5, v3
	v_add_u32_e32 v4, 1, v1
	v_cmp_ge_u32_e32 vcc, v3, v2
	s_nop 1
	v_cndmask_b32_e32 v1, v1, v4, vcc
	v_sub_u32_e32 v4, v3, v2
	v_cndmask_b32_e32 v3, v3, v4, vcc
	v_add_u32_e32 v4, 1, v1
	v_cmp_ge_u32_e32 vcc, v3, v2
	v_add_u32_e32 v3, 1, v5
	s_nop 0
	v_cndmask_b32_e32 v1, v1, v4, vcc
	v_mul_lo_u32 v4, v2, v1
	v_add_u32_e32 v2, v4, v2
	v_cmp_ne_u32_e32 vcc, v3, v2
	s_and_saveexec_b64 s[10:11], vcc
	s_xor_b64 s[10:11], exec, s[10:11]
	s_cbranch_execz .LBB0_155
	s_waitcnt lgkmcnt(0)
	v_mov_b32_e32 v0, 0x7100
	global_load_dword v0, v0, s[40:41] offset:1024 sc1
	s_add_u32 s16, s40, 0x7500
	s_addc_u32 s17, s41, 0
	s_waitcnt vmcnt(0)
	v_cmp_eq_u32_e32 vcc, v0, v1
	s_and_saveexec_b64 s[12:13], vcc
	s_cbranch_execz .LBB0_154
	s_add_u32 s14, s40, 0x4200
	s_addc_u32 s15, s41, 0
	s_mov_b32 s28, 1
	s_mov_b64 s[18:19], 0
	v_mov_b32_e32 v0, 0
	s_branch .LBB0_145
